# grid barrier: XCD leader no longer waits for its per-XCD release atomic before the closing barrier
# speedup vs baseline: 1.0089x; 1.0089x over previous
; __device__ __forceinline__ unsigned xb_add(unsigned* p, unsigned v) { return __hip_atomic_fetch_add(p, v, __ATOMIC_RELAXED, __HIP_MEMORY_SCOPE_AGENT); }
; __device__ __forceinline__ void xcd_barrier(const XcdBarrier& b) {
;     ...
;             __builtin_amdgcn_fence(__ATOMIC_ACQUIRE, "agent");
;             xb_add(&bar[XB_XGEN(b.x)], 1u);
;             asm volatile("s_waitcnt vmcnt(0)" ::: "memory");
.LBB0_115:
	s_or_b64 exec, exec, s[0:1]
	v_readlane_b32 s0, v255, 4
	v_readlane_b32 s1, v255, 5
	s_mov_b32 s3, s1
	s_add_i32 s2, s20, 0x900
	v_writelane_b32 v255, s0, 4
	v_mov_b32_e32 v2, 1
	s_waitcnt vmcnt(0) lgkmcnt(0)
	v_writelane_b32 v255, s1, 5
	s_lshl_b64 s[0:1], s[2:3], 2
	s_add_u32 s0, s34, s0
	s_addc_u32 s1, s35, s1
	v_mov_b64_e32 v[0:1], s[0:1]
	global_atomic_add v[0:1], v2, off

; __device__ __forceinline__ unsigned xb_add(unsigned* p, unsigned v) { return __hip_atomic_fetch_add(p, v, __ATOMIC_RELAXED, __HIP_MEMORY_SCOPE_AGENT); }
; __device__ __forceinline__ void xcd_barrier(const XcdBarrier& b) {
;     ...
;             __builtin_amdgcn_fence(__ATOMIC_ACQUIRE, "agent");
;             xb_add(&bar[XB_XGEN(b.x)], 1u);
;             asm volatile("s_waitcnt vmcnt(0)" ::: "memory");
.LBB0_307:
	s_or_b64 exec, exec, s[0:1]
	v_readlane_b32 s0, v255, 4
	v_readlane_b32 s1, v255, 5
	s_mov_b32 s5, s1
	s_add_i32 s4, s22, 0x900
	v_writelane_b32 v255, s0, 4
	v_mov_b32_e32 v2, 1
	s_waitcnt vmcnt(0) lgkmcnt(0)
	v_writelane_b32 v255, s1, 5
	s_lshl_b64 s[0:1], s[4:5], 2
	s_add_u32 s0, s34, s0
	s_addc_u32 s1, s35, s1
	v_mov_b64_e32 v[0:1], s[0:1]
	global_atomic_add v[0:1], v2, off

; __device__ __forceinline__ unsigned xb_add(unsigned* p, unsigned v) { return __hip_atomic_fetch_add(p, v, __ATOMIC_RELAXED, __HIP_MEMORY_SCOPE_AGENT); }
; __device__ __forceinline__ void xcd_barrier(const XcdBarrier& b) {
;     ...
;             __builtin_amdgcn_fence(__ATOMIC_ACQUIRE, "agent");
;             xb_add(&bar[XB_XGEN(b.x)], 1u);
;             asm volatile("s_waitcnt vmcnt(0)" ::: "memory");
.LBB0_856:
	s_or_b64 exec, exec, s[0:1]
	v_readlane_b32 s0, v255, 4
	v_readlane_b32 s1, v255, 5
	s_mov_b32 s3, s1
	s_add_i32 s2, s22, 0x900
	v_writelane_b32 v255, s0, 4
	v_mov_b32_e32 v2, 1
	s_waitcnt vmcnt(0) lgkmcnt(0)
	v_writelane_b32 v255, s1, 5
	s_lshl_b64 s[0:1], s[2:3], 2
	s_add_u32 s0, s36, s0
	s_addc_u32 s1, s37, s1
	v_mov_b64_e32 v[0:1], s[0:1]
	global_atomic_add v[0:1], v2, off
